# attention general-path bias addressing folded to add+min (pre-scaled base), 16 fewer VALU per masked tile; on top of packed-softmax version
# baseline (speedup 1.0000x reference)
; __device__ __forceinline__ void attn_wg_item(const Params& p, int item, LAS unsigned char* lds) {
;     ...
;     } else {
;       const int dbase = D0 + qi - r0 - 4 * kq + 64;
; #pragma unroll
;       for (int kt = 0; kt < 4; ++kt)
; #pragma unroll
;         for (int i = 0; i < 4; ++i) { int d = dbase - (16 * kt + i); d = d > 320 ? 320 : d;
;           float sv = S[kt][i] + bl[d]; if (r0 + 16 * kt + 4 * kq + i < rmin) sv = -1e30f; S[kt][i] = sv; tmax = fmaxf(tmax, sv); }
;     }
.LBB0_820:
	s_andn2_saveexec_b64 s[14:15], s[14:15]
	s_cbranch_execz .LBB0_822
	v_add_u32_e32 v130, s9, v111
	v_lshl_add_u32 v167, v130, 2, s37
	s_add_i32 s100, s37, 0x500
	v_add_u32_e32 v123, 256, v167
	v_min_i32_e32 v124, s100, v123
	v_add_u32_e32 v123, 248, v167
	v_min_i32_e32 v125, s100, v123
	v_add_u32_e32 v123, 244, v167
	v_min_i32_e32 v126, s100, v123
	v_add_u32_e32 v123, 192, v167
	v_min_i32_e32 v127, s100, v123
	v_add_u32_e32 v123, 188, v167
	v_min_i32_e32 v128, s100, v123
	v_add_u32_e32 v123, 184, v167
	v_add_u32_e32 v122, 252, v167
	v_min_i32_e32 v129, s100, v123
	v_add_u32_e32 v123, 180, v167
	v_min_i32_e32 v122, s100, v122
	v_add_u32_e32 v132, s18, v151
	v_min_i32_e32 v131, s100, v123
	ds_read_b32 v123, v122
	ds_read_b32 v122, v124
	ds_read_b32 v124, v125
	ds_read_b32 v125, v126
	ds_read_b32 v126, v127
	ds_read_b32 v127, v128
	ds_read_b32 v128, v129
	ds_read_b32 v129, v131
	s_waitcnt lgkmcnt(6)
	v_pk_add_f32 v[92:93], v[92:93], v[122:123]
	v_add_u32_e32 v122, 1, v132
	v_cmp_le_u32_e32 vcc, s36, v122
	s_waitcnt lgkmcnt(2)
	v_pk_add_f32 v[88:89], v[88:89], v[126:127]
	v_cndmask_b32_e32 v123, v146, v93, vcc
	v_cmp_le_u32_e32 vcc, s34, v132
	s_nop 1
	v_cndmask_b32_e32 v122, v146, v92, vcc
	v_pk_add_f32 v[92:93], v[94:95], v[124:125]
	v_or_b32_e32 v94, 3, v132
	v_or_b32_e32 v95, 2, v132
	v_cmp_le_u32_e32 vcc, s36, v94
	v_or_b32_e32 v94, 16, v132
	v_max_f32_e32 v131, 0xf149f2ca, v122
	v_cndmask_b32_e32 v125, v146, v93, vcc
	v_cmp_le_u32_e32 vcc, s34, v95
	v_or_b32_e32 v93, 17, v132
	v_add_u32_e32 v95, 56, v167
	v_cndmask_b32_e32 v124, v146, v92, vcc
	v_cmp_le_u32_e32 vcc, s36, v93
	v_max3_f32 v92, v131, v123, v124
	v_add_u32_e32 v93, 60, v167
	v_cndmask_b32_e32 v127, v146, v89, vcc
	v_cmp_le_u32_e32 vcc, s34, v94
	v_cndmask_b32_e32 v126, v146, v88, vcc
	s_waitcnt lgkmcnt(0)
	v_pk_add_f32 v[88:89], v[90:91], v[128:129]
	v_or_b32_e32 v90, 19, v132
	v_or_b32_e32 v91, 18, v132
	v_cmp_le_u32_e32 vcc, s36, v90
	v_max3_f32 v92, v92, v125, v126
	v_add_u32_e32 v90, 120, v167
	v_cndmask_b32_e32 v129, v146, v89, vcc
	v_cmp_le_u32_e32 vcc, s34, v91
	v_add_u32_e32 v89, 124, v167
	v_add_u32_e32 v91, 116, v167
	v_cndmask_b32_e32 v128, v146, v88, vcc
	v_max3_f32 v94, v92, v127, v128
	v_add_u32_e32 v88, 128, v167
	v_add_u32_e32 v92, 64, v167
	v_add_u32_e32 v130, 52, v167
	v_min_i32_e32 v88, s100, v88
	v_min_i32_e32 v89, s100, v89
	v_min_i32_e32 v90, s100, v90
	v_min_i32_e32 v91, s100, v91
	v_min_i32_e32 v92, s100, v92
	v_min_i32_e32 v93, s100, v93
	v_min_i32_e32 v95, s100, v95
	v_min_i32_e32 v130, s100, v130
	ds_read_b32 v88, v88
	ds_read_b32 v89, v89
	ds_read_b32 v90, v90
	ds_read_b32 v91, v91
	ds_read_b32 v92, v92
	ds_read_b32 v93, v93
	ds_read_b32 v95, v95
	ds_read_b32 v136, v130
	s_waitcnt lgkmcnt(6)
	v_pk_add_f32 v[84:85], v[84:85], v[88:89]
	v_or_b32_e32 v88, 33, v132
	v_or_b32_e32 v89, 32, v132
	v_cmp_le_u32_e32 vcc, s36, v88
	s_waitcnt lgkmcnt(2)
	v_pk_add_f32 v[134:135], v[80:81], v[92:93]
	s_waitcnt lgkmcnt(1)
	v_add_f32_e32 v157, v82, v95
	v_cndmask_b32_e32 v131, v146, v85, vcc
	v_cmp_le_u32_e32 vcc, s34, v89
	s_nop 1
	v_cndmask_b32_e32 v130, v146, v84, vcc
	v_pk_add_f32 v[84:85], v[86:87], v[90:91]
	v_or_b32_e32 v86, 35, v132
	v_or_b32_e32 v87, 34, v132
	v_cmp_le_u32_e32 vcc, s36, v86
	v_max3_f32 v88, v94, v129, v130
	s_nop 0
	v_cndmask_b32_e32 v133, v146, v85, vcc
	v_cmp_le_u32_e32 vcc, s34, v87
	s_nop 1
	v_cndmask_b32_e32 v132, v146, v84, vcc
	v_max3_f32 v84, v88, v131, v132
	v_max3_f32 v80, v84, v133, v134
	v_max3_f32 v158, v80, v135, v157
